# attention row-max exchange: last chain max3 issued into both swap operands, wait states filled by hoisted independent instructions
# baseline (speedup 1.0000x reference)
.LBB0_323:
	s_nop 10
	v_max3_f32 v0, v80, s18, v81
	v_max3_f32 v0, v0, v82, v83
	v_max3_f32 v0, v0, v84, v85
	v_max3_f32 v0, v0, v86, v87
	v_max3_f32 v0, v0, v88, v89
	v_max3_f32 v0, v0, v90, v91
	v_max3_f32 v0, v0, v92, v93
	v_max3_f32 v2, v0, v94, v95
	v_max3_f32 v255, v0, v94, v95
	s_and_b64 vcc, exec, s[38:39]
	s_waitcnt lgkmcnt(0)
	v_permlane32_swap_b32_e32 v2, v255
	v_max3_f32 v234, v231, v2, v255
	v_sub_f32_e32 v255, v234, v231
	v_cmp_lt_f32_e64 s[98:99], 4.0, v255
	s_nop 1
	v_cndmask_b32_e64 v234, v231, v234, s[98:99]
	v_sub_f32_e32 v2, v81, v234
	v_exp_f32_e32 v14, v2
	v_sub_f32_e32 v2, v82, v234
	v_exp_f32_e32 v232, v2
	v_sub_f32_e32 v2, v83, v234
	v_exp_f32_e32 v236, v2
	v_sub_f32_e32 v2, v84, v234
	v_exp_f32_e32 v237, v2
	v_sub_f32_e32 v2, v85, v234
	v_exp_f32_e32 v238, v2
	v_sub_f32_e32 v2, v86, v234
	v_exp_f32_e32 v239, v2
	v_sub_f32_e32 v2, v87, v234
	v_exp_f32_e32 v240, v2
	v_sub_f32_e32 v2, v88, v234
	v_exp_f32_e32 v241, v2
	v_sub_f32_e32 v2, v89, v234
	v_exp_f32_e32 v242, v2
	v_sub_f32_e32 v2, v90, v234
	v_exp_f32_e32 v243, v2
	v_sub_f32_e32 v2, v91, v234
	v_exp_f32_e32 v244, v2
	v_sub_f32_e32 v2, v92, v234
	v_exp_f32_e32 v245, v2
	v_sub_f32_e32 v2, v93, v234
	v_exp_f32_e32 v246, v2
	v_sub_f32_e32 v2, v94, v234
	v_sub_f32_e32 v0, v80, v234
	v_exp_f32_e32 v247, v2
	v_sub_f32_e32 v2, v95, v234
	v_mfma_f32_32x32x16_bf16 v[80:95], v[168:171], v[112:115], 0
	v_exp_f32_e32 v0, v0
	v_exp_f32_e32 v248, v2
	v_cvt_pk_bf16_f32 v6, v0, v14
	v_cvt_pk_bf16_f32 v7, v232, v236
	v_cvt_pk_bf16_f32 v8, v237, v238
	v_cvt_pk_bf16_f32 v9, v239, v240
	v_cvt_pk_bf16_f32 v2, v241, v242
	v_mfma_f32_32x32x16_bf16 v[80:95], v[164:167], v[116:119], v[80:95]
	v_cvt_pk_bf16_f32 v3, v243, v244
	v_cvt_pk_bf16_f32 v4, v245, v246
	v_cvt_pk_bf16_f32 v5, v247, v248
	v_mfma_f32_32x32x16_bf16 v[80:95], v[10:13], v[120:123], v[80:95]
	v_mfma_f32_32x32x16_bf16 v[80:95], v[160:163], v[124:127], v[80:95]
	s_cbranch_vccnz .LBB0_326
	s_cmp_lt_i32 s3, s62
	s_cselect_b64 s[0:1], -1, 0
	s_cmp_gt_i32 s3, s55
	s_cselect_b64 s[26:27], -1, 0
	s_or_b64 s[0:1], s[0:1], s[26:27]
	s_andn2_b64 vcc, exec, s[0:1]
	s_cbranch_vccnz .LBB0_326
	s_sub_i32 s0, s33, s63
	v_add_u32_e32 v10, s0, v214
	v_cmp_lt_u32_e32 vcc, s66, v10
	v_add_u32_e32 v255, s0, v215
	v_cmp_lt_u32_e64 s[26:27], s66, v255
	v_cndmask_b32_e32 v80, v200, v80, vcc
	v_add_u32_e32 v10, s0, v216
	v_cmp_lt_u32_e32 vcc, s66, v10
	v_cndmask_b32_e64 v81, v200, v81, s[26:27]
	v_add_u32_e32 v255, s0, v217
	v_cmp_lt_u32_e64 s[26:27], s66, v255
	v_cndmask_b32_e32 v82, v200, v82, vcc
	v_add_u32_e32 v10, s0, v218
	v_cmp_lt_u32_e32 vcc, s66, v10
	v_cndmask_b32_e64 v83, v200, v83, s[26:27]
	v_add_u32_e32 v255, s0, v219
	v_cmp_lt_u32_e64 s[26:27], s66, v255
	v_cndmask_b32_e32 v84, v200, v84, vcc
	v_add_u32_e32 v10, s0, v220
	v_cmp_lt_u32_e32 vcc, s66, v10
	v_cndmask_b32_e64 v85, v200, v85, s[26:27]
	v_add_u32_e32 v255, s0, v221
	v_cmp_lt_u32_e64 s[26:27], s66, v255
	v_cndmask_b32_e32 v86, v200, v86, vcc
	v_add_u32_e32 v10, s0, v222
	v_cmp_lt_u32_e32 vcc, s66, v10
	v_cndmask_b32_e64 v87, v200, v87, s[26:27]
	v_add_u32_e32 v255, s0, v223
	v_cmp_lt_u32_e64 s[26:27], s66, v255
	v_cndmask_b32_e32 v88, v200, v88, vcc
	v_add_u32_e32 v10, s0, v224
	v_cmp_lt_u32_e32 vcc, s66, v10
	v_cndmask_b32_e64 v89, v200, v89, s[26:27]
	v_add_u32_e32 v255, s0, v225
	v_cmp_lt_u32_e64 s[26:27], s66, v255
	v_cndmask_b32_e32 v90, v200, v90, vcc
	v_add_u32_e32 v10, s0, v226
	v_cmp_lt_u32_e32 vcc, s66, v10
	v_cndmask_b32_e64 v91, v200, v91, s[26:27]
	v_add_u32_e32 v255, s0, v227
	v_cmp_lt_u32_e64 s[26:27], s66, v255
	v_cndmask_b32_e32 v92, v200, v92, vcc
	v_add_u32_e32 v10, s0, v228
	v_cmp_lt_u32_e32 vcc, s66, v10
	v_cndmask_b32_e64 v93, v200, v93, s[26:27]
	v_add_u32_e32 v255, s0, v229
	v_cmp_lt_u32_e64 s[26:27], s66, v255
	v_cndmask_b32_e32 v94, v200, v94, vcc
	s_nop 0
	v_cndmask_b32_e64 v95, v200, v95, s[26:27]

.Lrs_0:
	v_max3_f32 v0, v80, s18, v81
	v_max3_f32 v0, v0, v82, v83
	v_max3_f32 v0, v0, v84, v85
	v_max3_f32 v0, v0, v86, v87
	v_max3_f32 v0, v0, v88, v89
	v_max3_f32 v0, v0, v90, v91
	v_max3_f32 v0, v0, v92, v93
	v_max3_f32 v10, v0, v94, v95
	v_max3_f32 v255, v0, v94, v95
	s_waitcnt lgkmcnt(0)
	s_nop 0
	v_permlane32_swap_b32_e32 v10, v255
	v_max3_f32 v14, v235, v10, v255
	v_sub_f32_e32 v255, v14, v235
	v_cmp_lt_f32_e64 s[98:99], 4.0, v255
	s_nop 1
	v_cndmask_b32_e64 v14, v235, v14, s[98:99]
	v_sub_f32_e32 v0, v80, v14
	v_exp_f32_e32 v11, v0
	v_sub_f32_e32 v12, v81, v14
	v_exp_f32_e32 v12, v12
	v_sub_f32_e32 v13, v82, v14
	v_exp_f32_e32 v13, v13
	v_sub_f32_e32 v80, v83, v14
	v_exp_f32_e32 v81, v80
	v_sub_f32_e32 v80, v84, v14
	v_add_f32_e32 v0, 0, v11
	v_exp_f32_e32 v82, v80
	v_sub_f32_e32 v80, v85, v14
	v_add_f32_e32 v0, v12, v0
	v_exp_f32_e32 v83, v80
	v_sub_f32_e32 v80, v86, v14
	v_add_f32_e32 v0, v13, v0
	v_exp_f32_e32 v84, v80
	v_sub_f32_e32 v80, v87, v14
	v_add_f32_e32 v0, v81, v0
	v_exp_f32_e32 v85, v80
	v_sub_f32_e32 v80, v88, v14
	v_add_f32_e32 v0, v82, v0
	v_exp_f32_e32 v86, v80
	v_sub_f32_e32 v80, v89, v14
	v_add_f32_e32 v0, v83, v0
	v_exp_f32_e32 v87, v80
	v_sub_f32_e32 v80, v90, v14
	v_add_f32_e32 v0, v84, v0
	v_exp_f32_e32 v88, v80
	v_sub_f32_e32 v80, v91, v14
	v_add_f32_e32 v0, v85, v0
	v_exp_f32_e32 v89, v80
	v_sub_f32_e32 v80, v92, v14
	v_add_f32_e32 v0, v86, v0
	v_exp_f32_e32 v90, v80
	v_sub_f32_e32 v80, v93, v14
	v_add_f32_e32 v0, v87, v0
	v_exp_f32_e32 v91, v80
	v_sub_f32_e32 v80, v94, v14
	v_add_f32_e32 v0, v88, v0
	v_exp_f32_e32 v92, v80
	v_sub_f32_e32 v80, v95, v14
	v_sub_f32_e32 v10, v235, v14
	v_add_f32_e32 v0, v89, v0
	v_exp_f32_e32 v93, v80
	v_add_f32_e32 v0, v90, v0
	v_add_f32_e32 v0, v91, v0
	v_add_f32_e32 v0, v92, v0
	v_add_f32_e32 v0, v93, v0
	s_mov_b64 vcc, s[98:99]
	s_cbranch_vccz .Lrse_1
	v_exp_f32_e32 v10, v10
	s_nop 0
	v_fmac_f32_e32 v0, v15, v10
	v_mul_f32_e32 v46, v10, v46
	v_mul_f32_e32 v47, v10, v47
	v_mul_f32_e32 v44, v10, v44
	v_mul_f32_e32 v45, v10, v45
	v_mul_f32_e32 v42, v10, v42
	v_mul_f32_e32 v43, v10, v43
	v_mul_f32_e32 v40, v10, v40
	v_mul_f32_e32 v41, v10, v41
	v_mul_f32_e32 v38, v10, v38
	v_mul_f32_e32 v39, v10, v39
	v_mul_f32_e32 v36, v10, v36
	v_mul_f32_e32 v37, v10, v37
	v_mul_f32_e32 v34, v10, v34
	v_mul_f32_e32 v35, v10, v35
	v_mul_f32_e32 v32, v10, v32
	v_mul_f32_e32 v33, v10, v33
	v_mul_f32_e32 v30, v10, v30
	v_mul_f32_e32 v31, v10, v31
	v_mul_f32_e32 v28, v10, v28
	v_mul_f32_e32 v29, v10, v29
	v_mul_f32_e32 v26, v10, v26
	v_mul_f32_e32 v27, v10, v27
	v_mul_f32_e32 v24, v10, v24
	v_mul_f32_e32 v25, v10, v25
	v_mul_f32_e32 v22, v10, v22
	v_mul_f32_e32 v23, v10, v23
	v_mul_f32_e32 v20, v10, v20
	v_mul_f32_e32 v21, v10, v21
	v_mul_f32_e32 v18, v10, v18
	v_mul_f32_e32 v19, v10, v19
	v_mul_f32_e32 v16, v10, v16
	v_mul_f32_e32 v17, v10, v17
	s_branch .Lrs_1

.LBB0_344:
	s_nop 10
	v_max3_f32 v2, v80, s18, v81
	v_max3_f32 v2, v2, v82, v83
	v_max3_f32 v2, v2, v84, v85
	v_max3_f32 v2, v2, v86, v87
	v_max3_f32 v2, v2, v88, v89
	v_max3_f32 v2, v2, v90, v91
	v_max3_f32 v2, v2, v92, v93
	v_max3_f32 v3, v2, v94, v95
	v_max3_f32 v255, v2, v94, v95
	s_and_b64 vcc, exec, s[40:41]
	s_waitcnt lgkmcnt(0)
	v_permlane32_swap_b32_e32 v3, v255
	v_max3_f32 v233, v234, v3, v255
	v_sub_f32_e32 v255, v233, v234
	v_cmp_lt_f32_e64 s[98:99], 4.0, v255
	s_nop 1
	v_cndmask_b32_e64 v233, v234, v233, s[98:99]
	v_sub_f32_e32 v2, v80, v233
	v_exp_f32_e32 v235, v2
	v_sub_f32_e32 v2, v81, v233
	v_exp_f32_e32 v236, v2
	v_sub_f32_e32 v2, v82, v233
	v_exp_f32_e32 v237, v2
	v_sub_f32_e32 v2, v83, v233
	v_exp_f32_e32 v238, v2
	v_sub_f32_e32 v2, v84, v233
	v_exp_f32_e32 v239, v2
	v_sub_f32_e32 v2, v85, v233
	v_exp_f32_e32 v240, v2
	v_sub_f32_e32 v2, v86, v233
	v_exp_f32_e32 v241, v2
	v_sub_f32_e32 v2, v87, v233
	v_exp_f32_e32 v242, v2
	v_sub_f32_e32 v2, v88, v233
	v_exp_f32_e32 v243, v2
	v_sub_f32_e32 v2, v89, v233
	v_exp_f32_e32 v244, v2
	v_sub_f32_e32 v2, v90, v233
	v_exp_f32_e32 v245, v2
	v_sub_f32_e32 v2, v91, v233
	v_exp_f32_e32 v246, v2
	v_sub_f32_e32 v2, v92, v233
	v_exp_f32_e32 v247, v2
	v_sub_f32_e32 v2, v93, v233
	v_exp_f32_e32 v248, v2
	v_sub_f32_e32 v2, v94, v233
	v_exp_f32_e32 v249, v2
	v_sub_f32_e32 v2, v95, v233
	v_mfma_f32_32x32x16_bf16 v[80:95], v[168:171], v[112:115], 0
	v_exp_f32_e32 v250, v2
	v_cvt_pk_bf16_f32 v6, v235, v236
	v_cvt_pk_bf16_f32 v7, v237, v238
	v_cvt_pk_bf16_f32 v8, v239, v240
	v_cvt_pk_bf16_f32 v9, v241, v242
	v_cvt_pk_bf16_f32 v2, v243, v244
	v_cvt_pk_bf16_f32 v3, v245, v246
	v_mfma_f32_32x32x16_bf16 v[80:95], v[164:167], v[116:119], v[80:95]
	v_cvt_pk_bf16_f32 v4, v247, v248
	v_cvt_pk_bf16_f32 v5, v249, v250
	v_mfma_f32_32x32x16_bf16 v[80:95], v[10:13], v[120:123], v[80:95]
	v_mfma_f32_32x32x16_bf16 v[80:95], v[160:163], v[124:127], v[80:95]
	s_cbranch_vccnz .LBB0_347
	s_cmp_lt_i32 s3, s62
	s_cselect_b64 s[0:1], -1, 0
	s_cmp_gt_i32 s3, s55
	s_cselect_b64 s[26:27], -1, 0
	s_or_b64 s[0:1], s[0:1], s[26:27]
	s_andn2_b64 vcc, exec, s[0:1]
	s_cbranch_vccnz .LBB0_347
	s_sub_i32 s0, s33, s63
	v_add_u32_e32 v10, s0, v214
	v_cmp_lt_u32_e32 vcc, s66, v10
	v_add_u32_e32 v255, s0, v215
	v_cmp_lt_u32_e64 s[26:27], s66, v255
	v_cndmask_b32_e32 v80, v200, v80, vcc
	v_add_u32_e32 v10, s0, v216
	v_cmp_lt_u32_e32 vcc, s66, v10
	v_cndmask_b32_e64 v81, v200, v81, s[26:27]
	v_add_u32_e32 v255, s0, v217
	v_cmp_lt_u32_e64 s[26:27], s66, v255
	v_cndmask_b32_e32 v82, v200, v82, vcc
	v_add_u32_e32 v10, s0, v218
	v_cmp_lt_u32_e32 vcc, s66, v10
	v_cndmask_b32_e64 v83, v200, v83, s[26:27]
	v_add_u32_e32 v255, s0, v219
	v_cmp_lt_u32_e64 s[26:27], s66, v255
	v_cndmask_b32_e32 v84, v200, v84, vcc
	v_add_u32_e32 v10, s0, v220
	v_cmp_lt_u32_e32 vcc, s66, v10
	v_cndmask_b32_e64 v85, v200, v85, s[26:27]
	v_add_u32_e32 v255, s0, v221
	v_cmp_lt_u32_e64 s[26:27], s66, v255
	v_cndmask_b32_e32 v86, v200, v86, vcc
	v_add_u32_e32 v10, s0, v222
	v_cmp_lt_u32_e32 vcc, s66, v10
	v_cndmask_b32_e64 v87, v200, v87, s[26:27]
	v_add_u32_e32 v255, s0, v223
	v_cmp_lt_u32_e64 s[26:27], s66, v255
	v_cndmask_b32_e32 v88, v200, v88, vcc
	v_add_u32_e32 v10, s0, v224
	v_cmp_lt_u32_e32 vcc, s66, v10
	v_cndmask_b32_e64 v89, v200, v89, s[26:27]
	v_add_u32_e32 v255, s0, v225
	v_cmp_lt_u32_e64 s[26:27], s66, v255
	v_cndmask_b32_e32 v90, v200, v90, vcc
	v_add_u32_e32 v10, s0, v226
	v_cmp_lt_u32_e32 vcc, s66, v10
	v_cndmask_b32_e64 v91, v200, v91, s[26:27]
	v_add_u32_e32 v255, s0, v227
	v_cmp_lt_u32_e64 s[26:27], s66, v255
	v_cndmask_b32_e32 v92, v200, v92, vcc
	v_add_u32_e32 v10, s0, v228
	v_cmp_lt_u32_e32 vcc, s66, v10
	v_cndmask_b32_e64 v93, v200, v93, s[26:27]
	v_add_u32_e32 v255, s0, v229
	v_cmp_lt_u32_e64 s[26:27], s66, v255
	v_cndmask_b32_e32 v94, v200, v94, vcc
	s_nop 0
	v_cndmask_b32_e64 v95, v200, v95, s[26:27]

.Lrs_2:
	v_max3_f32 v10, v80, s18, v81
	v_max3_f32 v10, v10, v82, v83
	v_max3_f32 v10, v10, v84, v85
	v_max3_f32 v10, v10, v86, v87
	v_max3_f32 v10, v10, v88, v89
	v_max3_f32 v10, v10, v90, v91
	v_max3_f32 v10, v10, v92, v93
	v_max3_f32 v11, v10, v94, v95
	v_max3_f32 v255, v10, v94, v95
	v_mov_b32_e32 v232, v160
	s_waitcnt lgkmcnt(0)
	v_permlane32_swap_b32_e32 v11, v255
	v_max3_f32 v161, v14, v11, v255
	v_sub_f32_e32 v255, v161, v14
	v_cmp_lt_f32_e64 s[98:99], 4.0, v255
	s_nop 1
	v_cndmask_b32_e64 v161, v14, v161, s[98:99]
	v_sub_f32_e32 v11, v80, v161
	v_exp_f32_e32 v11, v11
	v_sub_f32_e32 v13, v81, v161
	v_sub_f32_e32 v10, v14, v161
	v_exp_f32_e32 v13, v13
	v_sub_f32_e32 v14, v82, v161
	v_exp_f32_e32 v14, v14
	v_sub_f32_e32 v80, v83, v161
	v_exp_f32_e32 v81, v80
	v_sub_f32_e32 v80, v84, v161
	v_add_f32_e32 v12, 0, v11
	v_exp_f32_e32 v82, v80
	v_sub_f32_e32 v80, v85, v161
	v_add_f32_e32 v12, v13, v12
	v_exp_f32_e32 v83, v80
	v_sub_f32_e32 v80, v86, v161
	v_add_f32_e32 v12, v14, v12
	v_exp_f32_e32 v85, v80
	v_sub_f32_e32 v80, v87, v161
	v_add_f32_e32 v12, v81, v12
	v_exp_f32_e32 v86, v80
	v_sub_f32_e32 v80, v88, v161
	v_add_f32_e32 v12, v82, v12
	v_exp_f32_e32 v87, v80
	v_sub_f32_e32 v80, v89, v161
	v_add_f32_e32 v12, v83, v12
	v_exp_f32_e32 v88, v80
	v_sub_f32_e32 v80, v90, v161
	v_add_f32_e32 v12, v85, v12
	v_exp_f32_e32 v89, v80
	v_sub_f32_e32 v80, v91, v161
	v_add_f32_e32 v12, v86, v12
	v_exp_f32_e32 v90, v80
	v_sub_f32_e32 v80, v92, v161
	v_add_f32_e32 v12, v87, v12
	v_exp_f32_e32 v91, v80
	v_sub_f32_e32 v80, v93, v161
	v_add_f32_e32 v12, v88, v12
	v_exp_f32_e32 v92, v80
	v_sub_f32_e32 v80, v94, v161
	v_add_f32_e32 v12, v89, v12
	v_exp_f32_e32 v93, v80
	v_sub_f32_e32 v80, v95, v161
	v_add_f32_e32 v12, v90, v12
	v_exp_f32_e32 v94, v80
	v_add_f32_e32 v12, v91, v12
	v_add_f32_e32 v12, v92, v12
	v_add_f32_e32 v12, v93, v12
	v_add_f32_e32 v84, v94, v12
	s_mov_b64 vcc, s[98:99]
	s_cbranch_vccz .Lrse_3
	v_exp_f32_e32 v10, v10
	s_nop 0
	v_fmac_f32_e32 v84, v0, v10
	v_mul_f32_e32 v46, v10, v46
	v_mul_f32_e32 v47, v10, v47
	v_mul_f32_e32 v44, v10, v44
	v_mul_f32_e32 v45, v10, v45
	v_mul_f32_e32 v42, v10, v42
	v_mul_f32_e32 v43, v10, v43
	v_mul_f32_e32 v40, v10, v40
	v_mul_f32_e32 v41, v10, v41
	v_mul_f32_e32 v38, v10, v38
	v_mul_f32_e32 v39, v10, v39
	v_mul_f32_e32 v36, v10, v36
	v_mul_f32_e32 v37, v10, v37
	v_mul_f32_e32 v34, v10, v34
	v_mul_f32_e32 v35, v10, v35
	v_mul_f32_e32 v32, v10, v32
	v_mul_f32_e32 v33, v10, v33
	v_mul_f32_e32 v30, v10, v30
	v_mul_f32_e32 v31, v10, v31
	v_mul_f32_e32 v28, v10, v28
	v_mul_f32_e32 v29, v10, v29
	v_mul_f32_e32 v26, v10, v26
	v_mul_f32_e32 v27, v10, v27
	v_mul_f32_e32 v24, v10, v24
	v_mul_f32_e32 v25, v10, v25
	v_mul_f32_e32 v22, v10, v22
	v_mul_f32_e32 v23, v10, v23
	v_mul_f32_e32 v20, v10, v20
	v_mul_f32_e32 v21, v10, v21
	v_mul_f32_e32 v18, v10, v18
	v_mul_f32_e32 v19, v10, v19
	v_mul_f32_e32 v16, v10, v16
	v_mul_f32_e32 v17, v10, v17
	s_branch .Lrs_3

.LBB0_362:
	s_nop 10
	v_max3_f32 v2, v80, s18, v81
	v_max3_f32 v2, v2, v82, v83
	v_max3_f32 v2, v2, v84, v85
	v_max3_f32 v2, v2, v86, v87
	v_max3_f32 v2, v2, v88, v89
	v_max3_f32 v2, v2, v90, v91
	v_max3_f32 v2, v2, v92, v93
	v_max3_f32 v3, v2, v94, v95
	v_max3_f32 v255, v2, v94, v95
	s_and_b64 vcc, exec, s[40:41]
	s_waitcnt lgkmcnt(0)
	v_permlane32_swap_b32_e32 v3, v255
	v_max3_f32 v234, v233, v3, v255
	v_sub_f32_e32 v255, v234, v233
	v_cmp_lt_f32_e64 s[98:99], 4.0, v255
	s_nop 1
	v_cndmask_b32_e64 v234, v233, v234, s[98:99]
	v_sub_f32_e32 v2, v80, v234
	v_exp_f32_e32 v235, v2
	v_sub_f32_e32 v2, v81, v234
	v_exp_f32_e32 v236, v2
	v_sub_f32_e32 v2, v82, v234
	v_exp_f32_e32 v237, v2
	v_sub_f32_e32 v2, v83, v234
	v_exp_f32_e32 v238, v2
	v_sub_f32_e32 v2, v84, v234
	v_exp_f32_e32 v239, v2
	v_sub_f32_e32 v2, v85, v234
	v_exp_f32_e32 v240, v2
	v_sub_f32_e32 v2, v86, v234
	v_exp_f32_e32 v241, v2
	v_sub_f32_e32 v2, v87, v234
	v_exp_f32_e32 v242, v2
	v_sub_f32_e32 v2, v88, v234
	v_exp_f32_e32 v243, v2
	v_sub_f32_e32 v2, v89, v234
	v_exp_f32_e32 v244, v2
	v_sub_f32_e32 v2, v90, v234
	v_exp_f32_e32 v245, v2
	v_sub_f32_e32 v2, v91, v234
	v_exp_f32_e32 v246, v2
	v_sub_f32_e32 v2, v92, v234
	v_exp_f32_e32 v247, v2
	v_sub_f32_e32 v2, v93, v234
	v_exp_f32_e32 v248, v2
	v_sub_f32_e32 v2, v94, v234
	v_exp_f32_e32 v249, v2
	v_sub_f32_e32 v2, v95, v234
	v_mfma_f32_32x32x16_bf16 v[80:95], v[168:171], v[112:115], 0
	v_exp_f32_e32 v250, v2
	v_cvt_pk_bf16_f32 v6, v235, v236
	v_cvt_pk_bf16_f32 v7, v237, v238
	v_cvt_pk_bf16_f32 v8, v239, v240
	v_cvt_pk_bf16_f32 v9, v241, v242
	v_cvt_pk_bf16_f32 v2, v243, v244
	v_cvt_pk_bf16_f32 v3, v245, v246
	v_mfma_f32_32x32x16_bf16 v[80:95], v[164:167], v[116:119], v[80:95]
	v_cvt_pk_bf16_f32 v4, v247, v248
	v_cvt_pk_bf16_f32 v5, v249, v250
	v_mfma_f32_32x32x16_bf16 v[80:95], v[10:13], v[120:123], v[80:95]
	v_mfma_f32_32x32x16_bf16 v[80:95], v[160:163], v[124:127], v[80:95]
	s_cbranch_vccnz .LBB0_365
	s_cmp_lt_i32 s3, s62
	s_cselect_b64 s[0:1], -1, 0
	s_cmp_gt_i32 s3, s55
	s_cselect_b64 s[26:27], -1, 0
	s_or_b64 s[0:1], s[0:1], s[26:27]
	s_andn2_b64 vcc, exec, s[0:1]
	s_cbranch_vccnz .LBB0_365
	s_sub_i32 s0, s33, s63
	v_add_u32_e32 v10, s0, v214
	v_cmp_lt_u32_e32 vcc, s66, v10
	v_add_u32_e32 v255, s0, v215
	v_cmp_lt_u32_e64 s[26:27], s66, v255
	v_cndmask_b32_e32 v80, v200, v80, vcc
	v_add_u32_e32 v10, s0, v216
	v_cmp_lt_u32_e32 vcc, s66, v10
	v_cndmask_b32_e64 v81, v200, v81, s[26:27]
	v_add_u32_e32 v255, s0, v217
	v_cmp_lt_u32_e64 s[26:27], s66, v255
	v_cndmask_b32_e32 v82, v200, v82, vcc
	v_add_u32_e32 v10, s0, v218
	v_cmp_lt_u32_e32 vcc, s66, v10
	v_cndmask_b32_e64 v83, v200, v83, s[26:27]
	v_add_u32_e32 v255, s0, v219
	v_cmp_lt_u32_e64 s[26:27], s66, v255
	v_cndmask_b32_e32 v84, v200, v84, vcc
	v_add_u32_e32 v10, s0, v220
	v_cmp_lt_u32_e32 vcc, s66, v10
	v_cndmask_b32_e64 v85, v200, v85, s[26:27]
	v_add_u32_e32 v255, s0, v221
	v_cmp_lt_u32_e64 s[26:27], s66, v255
	v_cndmask_b32_e32 v86, v200, v86, vcc
	v_add_u32_e32 v10, s0, v222
	v_cmp_lt_u32_e32 vcc, s66, v10
	v_cndmask_b32_e64 v87, v200, v87, s[26:27]
	v_add_u32_e32 v255, s0, v223
	v_cmp_lt_u32_e64 s[26:27], s66, v255
	v_cndmask_b32_e32 v88, v200, v88, vcc
	v_add_u32_e32 v10, s0, v224
	v_cmp_lt_u32_e32 vcc, s66, v10
	v_cndmask_b32_e64 v89, v200, v89, s[26:27]
	v_add_u32_e32 v255, s0, v225
	v_cmp_lt_u32_e64 s[26:27], s66, v255
	v_cndmask_b32_e32 v90, v200, v90, vcc
	v_add_u32_e32 v10, s0, v226
	v_cmp_lt_u32_e32 vcc, s66, v10
	v_cndmask_b32_e64 v91, v200, v91, s[26:27]
	v_add_u32_e32 v255, s0, v227
	v_cmp_lt_u32_e64 s[26:27], s66, v255
	v_cndmask_b32_e32 v92, v200, v92, vcc
	v_add_u32_e32 v10, s0, v228
	v_cmp_lt_u32_e32 vcc, s66, v10
	v_cndmask_b32_e64 v93, v200, v93, s[26:27]
	v_add_u32_e32 v255, s0, v229
	v_cmp_lt_u32_e64 s[26:27], s66, v255
	v_cndmask_b32_e32 v94, v200, v94, vcc
	s_nop 0
	v_cndmask_b32_e64 v95, v200, v95, s[26:27]

.LBB0_378:
	s_nop 10
	v_max3_f32 v2, v80, s18, v81
	v_max3_f32 v2, v2, v82, v83
	v_max3_f32 v2, v2, v84, v85
	v_max3_f32 v2, v2, v86, v87
	v_max3_f32 v2, v2, v88, v89
	v_max3_f32 v2, v2, v90, v91
	v_max3_f32 v2, v2, v92, v93
	v_max3_f32 v3, v2, v94, v95
	v_max3_f32 v255, v2, v94, v95
	s_and_b64 vcc, exec, s[38:39]
	s_waitcnt lgkmcnt(0)
	v_permlane32_swap_b32_e32 v3, v255
	v_max3_f32 v231, v234, v3, v255
	v_sub_f32_e32 v255, v231, v234
	v_cmp_lt_f32_e64 s[98:99], 4.0, v255
	s_nop 1
	v_cndmask_b32_e64 v231, v234, v231, s[98:99]
	v_sub_f32_e32 v2, v80, v231
	v_exp_f32_e32 v15, v2
	v_sub_f32_e32 v2, v81, v231
	v_exp_f32_e32 v233, v2
	v_sub_f32_e32 v2, v82, v231
	v_exp_f32_e32 v235, v2
	v_sub_f32_e32 v2, v83, v231
	v_exp_f32_e32 v236, v2
	v_sub_f32_e32 v2, v84, v231
	v_exp_f32_e32 v237, v2
	v_sub_f32_e32 v2, v85, v231
	v_exp_f32_e32 v238, v2
	v_sub_f32_e32 v2, v86, v231
	v_exp_f32_e32 v239, v2
	v_sub_f32_e32 v2, v87, v231
	v_exp_f32_e32 v240, v2
	v_sub_f32_e32 v2, v88, v231
	v_exp_f32_e32 v241, v2
	v_sub_f32_e32 v2, v89, v231
	v_exp_f32_e32 v242, v2
	v_sub_f32_e32 v2, v90, v231
	v_exp_f32_e32 v243, v2
	v_sub_f32_e32 v2, v91, v231
	v_exp_f32_e32 v244, v2
	v_sub_f32_e32 v2, v92, v231
	v_exp_f32_e32 v245, v2
	v_sub_f32_e32 v2, v93, v231
	v_exp_f32_e32 v246, v2
	v_sub_f32_e32 v2, v94, v231
	v_exp_f32_e32 v247, v2
	v_sub_f32_e32 v2, v95, v231
	v_mfma_f32_32x32x16_bf16 v[80:95], v[168:171], v[112:115], 0
	v_exp_f32_e32 v248, v2
	v_cvt_pk_bf16_f32 v6, v15, v233
	v_cvt_pk_bf16_f32 v7, v235, v236
	v_cvt_pk_bf16_f32 v8, v237, v238
	v_cvt_pk_bf16_f32 v9, v239, v240
	v_cvt_pk_bf16_f32 v2, v241, v242
	v_cvt_pk_bf16_f32 v3, v243, v244
	v_mfma_f32_32x32x16_bf16 v[80:95], v[164:167], v[116:119], v[80:95]
	v_cvt_pk_bf16_f32 v4, v245, v246
	v_cvt_pk_bf16_f32 v5, v247, v248
	v_mfma_f32_32x32x16_bf16 v[80:95], v[10:13], v[120:123], v[80:95]
	v_mfma_f32_32x32x16_bf16 v[80:95], v[160:163], v[124:127], v[80:95]
	s_cbranch_vccnz .LBB0_381
	s_cmp_lt_i32 s3, s62
	s_cselect_b64 s[0:1], -1, 0
	s_cmp_gt_i32 s3, s55
	s_cselect_b64 s[26:27], -1, 0
	s_or_b64 s[0:1], s[0:1], s[26:27]
	s_andn2_b64 vcc, exec, s[0:1]
	s_cbranch_vccnz .LBB0_381
	s_sub_i32 s0, s2, s63
	v_add_u32_e32 v10, s0, v214
	v_cmp_lt_u32_e32 vcc, s66, v10
	v_add_u32_e32 v255, s0, v215
	v_cmp_lt_u32_e64 s[26:27], s66, v255
	v_cndmask_b32_e32 v80, v200, v80, vcc
	v_add_u32_e32 v10, s0, v216
	v_cmp_lt_u32_e32 vcc, s66, v10
	v_cndmask_b32_e64 v81, v200, v81, s[26:27]
	v_add_u32_e32 v255, s0, v217
	v_cmp_lt_u32_e64 s[26:27], s66, v255
	v_cndmask_b32_e32 v82, v200, v82, vcc
	v_add_u32_e32 v10, s0, v218
	v_cmp_lt_u32_e32 vcc, s66, v10
	v_cndmask_b32_e64 v83, v200, v83, s[26:27]
	v_add_u32_e32 v255, s0, v219
	v_cmp_lt_u32_e64 s[26:27], s66, v255
	v_cndmask_b32_e32 v84, v200, v84, vcc
	v_add_u32_e32 v10, s0, v220
	v_cmp_lt_u32_e32 vcc, s66, v10
	v_cndmask_b32_e64 v85, v200, v85, s[26:27]
	v_add_u32_e32 v255, s0, v221
	v_cmp_lt_u32_e64 s[26:27], s66, v255
	v_cndmask_b32_e32 v86, v200, v86, vcc
	v_add_u32_e32 v10, s0, v222
	v_cmp_lt_u32_e32 vcc, s66, v10
	v_cndmask_b32_e64 v87, v200, v87, s[26:27]
	v_add_u32_e32 v255, s0, v223
	v_cmp_lt_u32_e64 s[26:27], s66, v255
	v_cndmask_b32_e32 v88, v200, v88, vcc
	v_add_u32_e32 v10, s0, v224
	v_cmp_lt_u32_e32 vcc, s66, v10
	v_cndmask_b32_e64 v89, v200, v89, s[26:27]
	v_add_u32_e32 v255, s0, v225
	v_cmp_lt_u32_e64 s[26:27], s66, v255
	v_cndmask_b32_e32 v90, v200, v90, vcc
	v_add_u32_e32 v10, s0, v226
	v_cmp_lt_u32_e32 vcc, s66, v10
	v_cndmask_b32_e64 v91, v200, v91, s[26:27]
	v_add_u32_e32 v255, s0, v227
	v_cmp_lt_u32_e64 s[26:27], s66, v255
	v_cndmask_b32_e32 v92, v200, v92, vcc
	v_add_u32_e32 v10, s0, v228
	v_cmp_lt_u32_e32 vcc, s66, v10
	v_cndmask_b32_e64 v93, v200, v93, s[26:27]
	v_add_u32_e32 v255, s0, v229
	v_cmp_lt_u32_e64 s[26:27], s66, v255
	v_cndmask_b32_e32 v94, v200, v94, vcc
	s_nop 0
	v_cndmask_b32_e64 v95, v200, v95, s[26:27]

.Lrs_6:
	v_max3_f32 v10, v80, s18, v81
	v_max3_f32 v10, v10, v82, v83
	v_max3_f32 v10, v10, v84, v85
	v_max3_f32 v10, v10, v86, v87
	v_max3_f32 v10, v10, v88, v89
	v_max3_f32 v10, v10, v90, v91
	v_max3_f32 v10, v10, v92, v93
	v_max3_f32 v11, v10, v94, v95
	v_max3_f32 v255, v10, v94, v95
	s_waitcnt lgkmcnt(0)
	s_nop 0
	v_permlane32_swap_b32_e32 v11, v255
	v_max3_f32 v235, v14, v11, v255
	v_sub_f32_e32 v255, v235, v14
	v_cmp_lt_f32_e64 s[98:99], 4.0, v255
	s_nop 1
	v_cndmask_b32_e64 v235, v14, v235, s[98:99]
	v_sub_f32_e32 v11, v80, v235
	v_exp_f32_e32 v11, v11
	v_sub_f32_e32 v13, v81, v235
	v_sub_f32_e32 v10, v14, v235
	v_exp_f32_e32 v13, v13
	v_sub_f32_e32 v14, v82, v235
	v_exp_f32_e32 v14, v14
	v_sub_f32_e32 v15, v83, v235
	v_exp_f32_e32 v81, v15
	v_sub_f32_e32 v15, v84, v235
	v_add_f32_e32 v12, 0, v11
	v_exp_f32_e32 v82, v15
	v_sub_f32_e32 v15, v85, v235
	v_add_f32_e32 v12, v13, v12
	v_exp_f32_e32 v83, v15
	v_sub_f32_e32 v15, v86, v235
	v_add_f32_e32 v12, v14, v12
	v_exp_f32_e32 v84, v15
	v_sub_f32_e32 v15, v87, v235
	v_add_f32_e32 v12, v81, v12
	v_exp_f32_e32 v85, v15
	v_sub_f32_e32 v15, v88, v235
	v_add_f32_e32 v12, v82, v12
	v_exp_f32_e32 v86, v15
	v_sub_f32_e32 v15, v89, v235
	v_add_f32_e32 v12, v83, v12
	v_exp_f32_e32 v87, v15
	v_sub_f32_e32 v15, v90, v235
	v_add_f32_e32 v12, v84, v12
	v_exp_f32_e32 v88, v15
	v_sub_f32_e32 v15, v91, v235
	v_add_f32_e32 v12, v85, v12
	v_exp_f32_e32 v89, v15
	v_sub_f32_e32 v15, v92, v235
	v_add_f32_e32 v12, v86, v12
	v_exp_f32_e32 v90, v15
	v_sub_f32_e32 v15, v93, v235
	v_add_f32_e32 v12, v87, v12
	v_exp_f32_e32 v91, v15
	v_sub_f32_e32 v15, v94, v235
	v_add_f32_e32 v12, v88, v12
	v_exp_f32_e32 v92, v15
	v_sub_f32_e32 v15, v95, v235
	v_add_f32_e32 v12, v89, v12
	v_exp_f32_e32 v93, v15
	v_add_f32_e32 v12, v90, v12
	v_add_f32_e32 v12, v91, v12
	v_add_f32_e32 v12, v92, v12
	v_add_f32_e32 v15, v93, v12
	s_mov_b64 vcc, s[98:99]
	s_cbranch_vccz .Lrse_7
	v_exp_f32_e32 v10, v10
	s_nop 0
	v_fmac_f32_e32 v15, v0, v10
	v_mul_f32_e32 v46, v10, v46
	v_mul_f32_e32 v47, v10, v47
	v_mul_f32_e32 v44, v10, v44
	v_mul_f32_e32 v45, v10, v45
	v_mul_f32_e32 v42, v10, v42
	v_mul_f32_e32 v43, v10, v43
	v_mul_f32_e32 v40, v10, v40
	v_mul_f32_e32 v41, v10, v41
	v_mul_f32_e32 v38, v10, v38
	v_mul_f32_e32 v39, v10, v39
	v_mul_f32_e32 v36, v10, v36
	v_mul_f32_e32 v37, v10, v37
	v_mul_f32_e32 v34, v10, v34
	v_mul_f32_e32 v35, v10, v35
	v_mul_f32_e32 v32, v10, v32
	v_mul_f32_e32 v33, v10, v33
	v_mul_f32_e32 v30, v10, v30
	v_mul_f32_e32 v31, v10, v31
	v_mul_f32_e32 v28, v10, v28
	v_mul_f32_e32 v29, v10, v29
	v_mul_f32_e32 v26, v10, v26
	v_mul_f32_e32 v27, v10, v27
	v_mul_f32_e32 v24, v10, v24
	v_mul_f32_e32 v25, v10, v25
	v_mul_f32_e32 v22, v10, v22
	v_mul_f32_e32 v23, v10, v23
	v_mul_f32_e32 v20, v10, v20
	v_mul_f32_e32 v21, v10, v21
	v_mul_f32_e32 v18, v10, v18
	v_mul_f32_e32 v19, v10, v19
	v_mul_f32_e32 v16, v10, v16
	v_mul_f32_e32 v17, v10, v17
	s_branch .Lrs_7
